# v32 + first MLA QK group also in S0S0S1S1 order
# speedup vs baseline: 1.0109x; 1.0109x over previous
.LBB0_2904:
	v_add_u32_e32 v0, s28, v183
	ds_read_b128 v[2:5], v0 offset:24576
	ds_read_b128 v[6:9], v0 offset:28672
	ds_read_b128 v[10:13], v0 offset:32768
	ds_read_b128 v[184:187], v0 offset:36864
	v_exp_f32_e32 v14, v96
	v_exp_f32_e32 v190, v97
	v_exp_f32_e32 v98, v98
	v_exp_f32_e32 v192, v99
	v_exp_f32_e32 v15, v100
	v_exp_f32_e32 v191, v101
	v_exp_f32_e32 v99, v102
	v_exp_f32_e32 v193, v103
	v_add_u32_e32 v0, s28, v182
	v_pk_add_f32 v[96:97], v[14:15], v[190:191]
	v_pk_add_f32 v[100:101], v[98:99], v[192:193]
	s_nop 0
	v_pk_add_f32 v[96:97], v[96:97], v[100:101]
	v_cvt_pk_bf16_f32 v99, v99, v193
	v_pk_add_f32 v[202:203], v[96:97], v[96:97] op_sel_hi:[0,1]
	v_cvt_pk_bf16_f32 v96, v14, v190
	v_cvt_pk_bf16_f32 v97, v98, v192
	v_cvt_pk_bf16_f32 v98, v15, v191
	ds_read_b128 v[100:103], v0 offset:24576
	ds_read_b128 v[190:193], v0 offset:28672
	ds_read_b128 v[194:197], v0 offset:32768
	ds_read_b128 v[198:201], v0 offset:36864
	s_waitcnt lgkmcnt(0)
	v_mfma_f32_32x32x16_bf16 v[64:79], v[2:5], v[96:99], v[64:79]
	v_mfma_f32_32x32x16_bf16 v[48:63], v[6:9], v[96:99], v[48:63]
	v_mfma_f32_32x32x16_bf16 v[32:47], v[10:13], v[96:99], v[32:47]
	v_mfma_f32_32x32x16_bf16 v[16:31], v[184:187], v[96:99], v[16:31]
	v_exp_f32_e32 v2, v104
	v_exp_f32_e32 v4, v105
	v_exp_f32_e32 v3, v106
	v_exp_f32_e32 v5, v107
	v_exp_f32_e32 v6, v108
	v_exp_f32_e32 v8, v109
	v_exp_f32_e32 v7, v110
	v_exp_f32_e32 v9, v111
	v_pk_add_f32 v[10:11], v[2:3], v[4:5]
	v_add_u32_e32 v0, s28, v180
	v_pk_add_f32 v[14:15], v[10:11], v[10:11] op_sel_hi:[0,1]
	v_pk_add_f32 v[10:11], v[6:7], v[8:9]
	v_cvt_pk_bf16_f32 v2, v2, v4
	v_pk_add_f32 v[184:185], v[10:11], v[10:11] op_sel_hi:[0,1]
	v_cvt_pk_bf16_f32 v3, v3, v5
	v_cvt_pk_bf16_f32 v4, v6, v8
	v_cvt_pk_bf16_f32 v5, v7, v9
	ds_read_b128 v[6:9], v0 offset:24576
	ds_read_b128 v[10:13], v0 offset:28672
	ds_read_b128 v[96:99], v0 offset:32768
	ds_read_b128 v[104:107], v0 offset:36864
	v_mfma_f32_32x32x16_bf16 v[64:79], v[100:103], v[2:5], v[64:79]
	v_mfma_f32_32x32x16_bf16 v[48:63], v[190:193], v[2:5], v[48:63]
	v_mfma_f32_32x32x16_bf16 v[32:47], v[194:197], v[2:5], v[32:47]
	v_mfma_f32_32x32x16_bf16 v[16:31], v[198:201], v[2:5], v[16:31]
	v_exp_f32_e32 v0, v80
	v_exp_f32_e32 v2, v81
	v_exp_f32_e32 v3, v82
	v_exp_f32_e32 v4, v83
	v_exp_f32_e32 v5, v84
	v_exp_f32_e32 v14, v85
	v_exp_f32_e32 v80, v86
	v_exp_f32_e32 v81, v87
	v_add_f32_e32 v187, v0, v2
	v_cvt_pk_bf16_f32 v2, v0, v2
	v_add_u32_e32 v0, s28, v175
	v_add_f32_e32 v191, v3, v4
	v_add_f32_e32 v193, v5, v14
	v_add_f32_e32 v195, v80, v81
	v_cvt_pk_bf16_f32 v3, v3, v4
	v_cvt_pk_bf16_f32 v4, v5, v14
	v_cvt_pk_bf16_f32 v5, v80, v81
	ds_read_b128 v[80:83], v0 offset:24576
	ds_read_b128 v[84:87], v0 offset:28672
	ds_read_b128 v[100:103], v0 offset:32768
	ds_read_b128 v[108:111], v0 offset:36864
	s_waitcnt lgkmcnt(0)
	v_mfma_f32_32x32x16_bf16 v[64:79], v[6:9], v[2:5], v[64:79]
	v_mfma_f32_32x32x16_bf16 v[48:63], v[10:13], v[2:5], v[48:63]
	v_mfma_f32_32x32x16_bf16 v[32:47], v[96:99], v[2:5], v[32:47]
	v_mfma_f32_32x32x16_bf16 v[16:31], v[104:107], v[2:5], v[16:31]
	v_exp_f32_e32 v186, v88
	v_exp_f32_e32 v190, v89
	v_exp_f32_e32 v192, v90
	v_exp_f32_e32 v194, v91
	v_exp_f32_e32 v14, v92
	v_exp_f32_e32 v184, v93
	v_exp_f32_e32 v202, v94
	v_exp_f32_e32 v0, v95
	v_cvt_pk_bf16_f32 v2, v186, v190
	v_cvt_pk_bf16_f32 v3, v192, v194
	v_cvt_pk_bf16_f32 v4, v14, v184
	v_cvt_pk_bf16_f32 v5, v202, v0
	s_nop 1
	v_mfma_f32_32x32x16_bf16 v[64:79], v[80:83], v[2:5], v[64:79]
	v_add_f32_e64 v6, v186, v190
	v_add_f32_e64 v7, v187, v191
	v_add_f32_e64 v8, v192, v194
	v_add_f32_e64 v9, v193, v195
	v_add_f32_e64 v10, v202, v0
	v_add_f32_e64 v11, v203, v1
	v_pk_add_f32 v[6:7], v[6:7], v[8:9]
	v_pk_add_f32 v[8:9], v[14:15], v[184:185]
	s_nop 0
	v_pk_add_f32 v[8:9], v[8:9], v[10:11]
	v_mfma_f32_32x32x16_bf16 v[48:63], v[84:87], v[2:5], v[48:63]
	v_add_f32_e64 v6, v6, v8
	v_add_f32_e64 v7, v7, v9
	v_pk_add_f32 v[6:7], v[6:7], v[6:7] op_sel:[0,1] op_sel_hi:[1,0]
	v_mfma_f32_32x32x16_bf16 v[32:47], v[100:103], v[2:5], v[32:47]
	v_mfma_f32_32x32x16_bf16 v[16:31], v[108:111], v[2:5], v[16:31]
	v_mov_b32_e32 v0, v6
	s_nop 1
	v_permlane32_swap_b32_e32 v6, v0
	v_add_f32_e32 v0, v6, v0
	v_add_f32_e32 v171, v171, v0
	v_add_u32_e32 v0, s1, v174
	v_add_u32_e32 v14, s1, v173
	v_add_u32_e32 v15, s1, v170
	ds_read_b128 v[2:5], v0
	ds_read_b128 v[6:9], v0 offset:12288
	ds_read_b128 v[10:13], v14
	ds_read_b128 v[184:187], v14 offset:12288
	v_add_u32_e32 v206, s1, v172
	ds_read_b128 v[190:193], v15
	ds_read_b128 v[194:197], v15 offset:12288
	ds_read_b128 v[198:201], v206
	ds_read_b128 v[202:205], v206 offset:12288
	v_xor_b32_e32 v80, 0x80000000, v181
	v_mov_b32_e32 v81, v80
	v_mov_b32_e32 v82, v80
	v_mov_b32_e32 v83, v80
	v_mov_b32_e32 v84, v80
	v_mov_b32_e32 v85, v80
	v_mov_b32_e32 v86, v80
	v_mov_b32_e32 v87, v80
	v_mov_b32_e32 v88, v80
	v_mov_b32_e32 v89, v80
	v_mov_b32_e32 v90, v80
	v_mov_b32_e32 v91, v80
	v_mov_b32_e32 v92, v80
	v_mov_b32_e32 v93, v80
	v_mov_b32_e32 v94, v80
	v_mov_b32_e32 v95, v80
	s_waitcnt lgkmcnt(0)
	s_nop 0
	v_mfma_f32_32x32x16_bf16 v[96:111], v[2:5], v[112:115], v[80:95]
	v_mfma_f32_32x32x16_bf16 v[96:111], v[10:13], v[116:119], v[96:111]
	v_mfma_f32_32x32x16_bf16 v[80:95], v[6:9], v[112:115], v[80:95]
	v_mfma_f32_32x32x16_bf16 v[80:95], v[184:187], v[116:119], v[80:95]
	ds_read_b128 v[2:5], v14 offset:12416
	ds_read_b128 v[6:9], v14 offset:128
	ds_read_b128 v[10:13], v0 offset:12416
	ds_read_b128 v[184:187], v0 offset:128
	v_mfma_f32_32x32x16_bf16 v[96:111], v[190:193], v[120:123], v[96:111]
	v_mfma_f32_32x32x16_bf16 v[96:111], v[198:201], v[124:127], v[96:111]
	v_mfma_f32_32x32x16_bf16 v[80:95], v[194:197], v[120:123], v[80:95]
	v_mfma_f32_32x32x16_bf16 v[80:95], v[202:205], v[124:127], v[80:95]
	ds_read_b128 v[190:193], v15 offset:128
	ds_read_b128 v[194:197], v15 offset:12416
	ds_read_b128 v[198:201], v206 offset:128
	ds_read_b128 v[202:205], v206 offset:12416
	s_waitcnt lgkmcnt(0)
	v_mfma_f32_32x32x16_bf16 v[96:111], v[184:187], v[128:131], v[96:111]
	v_mfma_f32_32x32x16_bf16 v[96:111], v[6:9], v[132:135], v[96:111]
	v_mfma_f32_32x32x16_bf16 v[80:95], v[10:13], v[128:131], v[80:95]
	v_mfma_f32_32x32x16_bf16 v[80:95], v[2:5], v[132:135], v[80:95]
	ds_read_b128 v[2:5], v14 offset:12544
	ds_read_b128 v[6:9], v14 offset:256
	ds_read_b128 v[10:13], v0 offset:12544
	ds_read_b128 v[184:187], v0 offset:256
	v_mfma_f32_32x32x16_bf16 v[96:111], v[190:193], v[136:139], v[96:111]
	v_mfma_f32_32x32x16_bf16 v[96:111], v[198:201], v[140:143], v[96:111]
	v_mfma_f32_32x32x16_bf16 v[80:95], v[194:197], v[136:139], v[80:95]
	v_mfma_f32_32x32x16_bf16 v[80:95], v[202:205], v[140:143], v[80:95]
	ds_read_b128 v[190:193], v15 offset:256
	ds_read_b128 v[194:197], v15 offset:12544
	ds_read_b128 v[198:201], v206 offset:256
	ds_read_b128 v[202:205], v206 offset:12544
	s_waitcnt lgkmcnt(0)
	v_mfma_f32_32x32x16_bf16 v[96:111], v[184:187], v[144:147], v[96:111]
	v_mfma_f32_32x32x16_bf16 v[96:111], v[6:9], v[148:151], v[96:111]
	v_mfma_f32_32x32x16_bf16 v[80:95], v[10:13], v[144:147], v[80:95]
	v_mfma_f32_32x32x16_bf16 v[80:95], v[2:5], v[148:151], v[80:95]
	v_mfma_f32_32x32x16_bf16 v[96:111], v[190:193], v[152:155], v[96:111]
	v_mfma_f32_32x32x16_bf16 v[96:111], v[198:201], v[156:159], v[96:111]
	v_mfma_f32_32x32x16_bf16 v[80:95], v[194:197], v[152:155], v[80:95]
	s_nop 10
	v_max_f32_e32 v0, v97, v97
	v_max_f32_e32 v2, v96, v96
	v_max_f32_e32 v0, v2, v0
	v_max3_f32 v0, v0, v98, v99
	v_max3_f32 v0, v0, v100, v101
	v_max3_f32 v0, v0, v102, v103
	v_max3_f32 v0, v0, v104, v105
	v_mfma_f32_32x32x16_bf16 v[80:95], v[202:205], v[156:159], v[80:95]
	v_max3_f32 v0, v0, v106, v107
	v_max3_f32 v0, v0, v108, v109
	v_max3_f32 v0, v0, v110, v111
	s_mov_b32 s28, 0x41000000
	s_nop 7
	v_max3_f32 v0, v0, v80, v81
	v_max3_f32 v0, v0, v82, v83
	v_max3_f32 v0, v0, v84, v85
	v_max3_f32 v0, v0, v86, v87
	v_max3_f32 v0, v0, v88, v89
	v_max3_f32 v0, v0, v90, v91
	v_max3_f32 v0, v0, v92, v93
	v_max3_f32 v0, v0, v94, v95
	v_mov_b32_e32 v2, v0
	s_nop 1
	v_permlane32_swap_b32_e32 v0, v2
	v_max_f32_e32 v2, v2, v2
	v_max_f32_e32 v0, v0, v0
	v_max_f32_e32 v0, v0, v2
	v_cmp_ge_f32_e32 vcc, s28, v0
	s_cmp_eq_u64 vcc, exec
	s_cbranch_scc1 .LBB0_2906
	v_max_f32_e32 v0, v0, v0
	v_max_f32_e32 v2, 0, v0
	v_exp_f32_e64 v0, -v2
	v_add_f32_e32 v181, v181, v2
	v_sub_f32_e32 v111, v111, v2
	v_sub_f32_e32 v110, v110, v2
	v_pk_mul_f32 v[78:79], v[78:79], v[0:1] op_sel_hi:[1,0]
	v_pk_mul_f32 v[76:77], v[76:77], v[0:1] op_sel_hi:[1,0]
	v_pk_mul_f32 v[74:75], v[74:75], v[0:1] op_sel_hi:[1,0]
	v_pk_mul_f32 v[72:73], v[72:73], v[0:1] op_sel_hi:[1,0]
	v_pk_mul_f32 v[70:71], v[70:71], v[0:1] op_sel_hi:[1,0]
	v_pk_mul_f32 v[68:69], v[68:69], v[0:1] op_sel_hi:[1,0]
	v_pk_mul_f32 v[66:67], v[66:67], v[0:1] op_sel_hi:[1,0]
	v_pk_mul_f32 v[64:65], v[64:65], v[0:1] op_sel_hi:[1,0]
	v_pk_mul_f32 v[62:63], v[62:63], v[0:1] op_sel_hi:[1,0]
	v_pk_mul_f32 v[60:61], v[60:61], v[0:1] op_sel_hi:[1,0]
	v_pk_mul_f32 v[58:59], v[58:59], v[0:1] op_sel_hi:[1,0]
	v_pk_mul_f32 v[56:57], v[56:57], v[0:1] op_sel_hi:[1,0]
	v_pk_mul_f32 v[54:55], v[54:55], v[0:1] op_sel_hi:[1,0]
	v_pk_mul_f32 v[52:53], v[52:53], v[0:1] op_sel_hi:[1,0]
	v_pk_mul_f32 v[50:51], v[50:51], v[0:1] op_sel_hi:[1,0]
	v_pk_mul_f32 v[48:49], v[48:49], v[0:1] op_sel_hi:[1,0]
	v_pk_mul_f32 v[46:47], v[46:47], v[0:1] op_sel_hi:[1,0]
	v_pk_mul_f32 v[44:45], v[44:45], v[0:1] op_sel_hi:[1,0]
	v_pk_mul_f32 v[42:43], v[42:43], v[0:1] op_sel_hi:[1,0]
	v_pk_mul_f32 v[40:41], v[40:41], v[0:1] op_sel_hi:[1,0]
	v_pk_mul_f32 v[38:39], v[38:39], v[0:1] op_sel_hi:[1,0]
	v_pk_mul_f32 v[36:37], v[36:37], v[0:1] op_sel_hi:[1,0]
	v_pk_mul_f32 v[34:35], v[34:35], v[0:1] op_sel_hi:[1,0]
	v_pk_mul_f32 v[32:33], v[32:33], v[0:1] op_sel_hi:[1,0]
	v_pk_mul_f32 v[30:31], v[30:31], v[0:1] op_sel_hi:[1,0]
	v_pk_mul_f32 v[28:29], v[28:29], v[0:1] op_sel_hi:[1,0]
	v_pk_mul_f32 v[26:27], v[26:27], v[0:1] op_sel_hi:[1,0]
	v_pk_mul_f32 v[24:25], v[24:25], v[0:1] op_sel_hi:[1,0]
	v_pk_mul_f32 v[22:23], v[22:23], v[0:1] op_sel_hi:[1,0]
	v_pk_mul_f32 v[20:21], v[20:21], v[0:1] op_sel_hi:[1,0]
	v_pk_mul_f32 v[18:19], v[18:19], v[0:1] op_sel_hi:[1,0]
	v_pk_mul_f32 v[16:17], v[16:17], v[0:1] op_sel_hi:[1,0]
	v_sub_f32_e32 v109, v109, v2
	v_sub_f32_e32 v108, v108, v2
	v_sub_f32_e32 v107, v107, v2
	v_sub_f32_e32 v106, v106, v2
	v_sub_f32_e32 v105, v105, v2
	v_sub_f32_e32 v104, v104, v2
	v_sub_f32_e32 v103, v103, v2
	v_sub_f32_e32 v102, v102, v2
	v_sub_f32_e32 v101, v101, v2
	v_sub_f32_e32 v100, v100, v2
	v_sub_f32_e32 v99, v99, v2
	v_sub_f32_e32 v98, v98, v2
	v_sub_f32_e32 v97, v97, v2
	v_sub_f32_e32 v96, v96, v2
	v_sub_f32_e32 v95, v95, v2
	v_sub_f32_e32 v94, v94, v2
	v_sub_f32_e32 v93, v93, v2
	v_sub_f32_e32 v92, v92, v2
	v_sub_f32_e32 v91, v91, v2
	v_sub_f32_e32 v90, v90, v2
	v_sub_f32_e32 v89, v89, v2
	v_sub_f32_e32 v88, v88, v2
	v_sub_f32_e32 v87, v87, v2
	v_sub_f32_e32 v86, v86, v2
	v_sub_f32_e32 v85, v85, v2
	v_sub_f32_e32 v84, v84, v2
	v_sub_f32_e32 v83, v83, v2
	v_sub_f32_e32 v82, v82, v2
	v_sub_f32_e32 v81, v81, v2
	v_sub_f32_e32 v80, v80, v2
	v_mul_f32_e32 v171, v171, v0
